# attention items: the static s_setprio 1 now applies to waves 4-7 only (scalar branch); hipcc had lowered it unconditionally
# speedup vs baseline: 1.0067x; 1.0067x over previous
.LBB0_725:
	s_and_b32 s13, s7, 1
	s_and_b32 s12, s6, 3
	s_lshl_b32 s11, s13, 13
	s_and_b64 s[2:3], exec, s[4:5]
	s_cselect_b32 s2, s13, s8
	s_cselect_b32 s3, 0x4000, s11
	s_lshl_b32 s2, s2, 8
	s_or_b32 s14, s2, s3
	s_cmp_lt_i32 s9, 1
	s_mov_b64 s[6:7], -1
	s_cbranch_scc1 .LBB0_766
	s_cmp_lg_u32 s9, 1
	s_cbranch_scc0 .LBB0_751
	s_lshl_b32 s2, s12, 7
	s_load_dwordx2 s[34:35], s[0:1], 0xe0
	s_add_u32 s2, s68, s2
	v_readlane_b32 s6, v254, 50
	s_addc_u32 s3, s69, 0
	s_or_b32 s6, s12, s6
	s_ashr_i32 s7, s6, 31
	s_lshl_b64 s[6:7], s[6:7], 2
	s_waitcnt lgkmcnt(0)
	s_add_u32 s6, s34, s6
	s_addc_u32 s7, s35, s7
	s_waitcnt vmcnt(0)
	v_mov_b32_e32 v8, v156
	global_load_dword v9, v1, s[6:7]
	s_nop 0
	v_ashrrev_i32_e32 v4, 6, v8
	v_and_b32_e32 v6, 31, v8
	v_lshlrev_b32_e32 v7, 5, v4
	v_or_b32_e32 v0, s14, v6
	v_add_u32_e32 v128, v0, v7
	v_ashrrev_i32_e32 v129, 31, v128
	v_bfe_u32 v140, v8, 5, 1
	v_lshlrev_b64 v[2:3], 10, v[128:129]
	v_lshl_add_u64 v[2:3], s[2:3], 0, v[2:3]
	v_lshlrev_b32_e32 v0, 4, v140
	v_lshl_add_u64 v[2:3], v[2:3], 0, v[0:1]
	global_load_dwordx4 v[96:99], v[2:3], off
	global_load_dwordx4 v[100:103], v[2:3], off offset:32
	global_load_dwordx4 v[104:107], v[2:3], off offset:64
	global_load_dwordx4 v[108:111], v[2:3], off offset:96
	v_cmp_lt_i32_e32 vcc, 3, v4
	s_and_saveexec_b64 s[2:3], vcc
	s_cbranch_execz .Lprio_skip_1
	s_setprio 1
.Lprio_skip_1:
	s_or_b64 exec, exec, s[2:3]
	s_lshl_b32 s6, s8, 2
	s_min_u32 s2, s6, 0x7a
	s_add_i32 s7, s2, 6
	v_sub_u32_e64 v0, s6, 2 clamp
	s_and_b64 s[2:3], exec, s[4:5]
	v_readfirstlane_b32 s2, v0
	s_cselect_b32 s15, 0, s2
	s_cselect_b32 s7, 0, s7
	s_sub_i32 s34, s7, s15
	s_cmp_lt_i32 s34, 1
	s_mov_b64 s[2:3], -1
	s_cbranch_scc0 .LBB0_731
	s_lshl_b32 s2, s13, 8
	s_lshl_b32 s3, s34, 6
	s_sub_i32 s2, s2, s3
	s_add_i32 s8, s2, 0x4000
	s_sub_i32 s44, 0x2000, s3
	s_mov_b64 s[2:3], 0

.LBB0_751:
	s_and_b64 vcc, exec, s[6:7]
	s_cbranch_vccz .LBB0_765
	s_waitcnt vmcnt(1)
	v_mov_b32_e32 v3, v156
	s_lshl_b32 s8, s12, 6
	v_and_b32_e32 v2, 31, v3
	s_waitcnt vmcnt(0)
	v_ashrrev_i32_e32 v6, 6, v3
	v_or_b32_e32 v0, s14, v2
	s_lshl_b32 s2, s12, 7
	v_lshl_add_u32 v128, v6, 5, v0
	s_add_u32 s2, s94, s2
	v_ashrrev_i32_e32 v129, 31, v128
	s_addc_u32 s3, s95, 0
	v_bfe_u32 v140, v3, 5, 1
	v_lshlrev_b64 v[4:5], 10, v[128:129]
	v_lshl_add_u64 v[4:5], s[2:3], 0, v[4:5]
	v_lshlrev_b32_e32 v0, 4, v140
	v_lshl_add_u64 v[4:5], v[4:5], 0, v[0:1]
	global_load_dwordx4 v[112:115], v[4:5], off
	global_load_dwordx4 v[108:111], v[4:5], off offset:32
	global_load_dwordx4 v[104:107], v[4:5], off offset:64
	global_load_dwordx4 v[100:103], v[4:5], off offset:96
	v_cmp_lt_i32_e32 vcc, 3, v6
	s_and_saveexec_b64 s[2:3], vcc
	s_cbranch_execz .Lprio_skip_2
	s_setprio 1
.Lprio_skip_2:
	s_or_b64 exec, exec, s[2:3]
	s_lshl_b32 s2, s12, 5
	s_and_b32 s2, s2, 64
	s_lshl_b32 s3, s2, 1
	v_readlane_b32 s6, v254, 38
	s_add_u32 s6, s6, s3
	v_readlane_b32 s3, v254, 39
	s_addc_u32 s7, s3, 0
	s_lshl_b32 s3, s13, 7
	s_or_b32 s2, s2, s3
	s_mulk_i32 s2, 0x4200
	s_add_u32 s34, s93, s2
	v_ashrrev_i32_e32 v0, 31, v3
	s_addc_u32 s35, s37, 0
	v_lshrrev_b32_e32 v0, 29, v0
	s_lshl_b32 s9, s13, 8
	v_add_u32_e32 v0, v3, v0
	s_or_b32 s2, s9, 0x4000
	v_ashrrev_i32_e32 v121, 3, v0
	v_and_b32_e32 v0, -8, v0
	s_and_b64 s[52:53], exec, s[4:5]
	v_sub_u32_e32 v28, v3, v0
	s_cselect_b32 s15, s2, s11
	v_add_u32_e32 v4, s15, v121
	v_lshlrev_b32_e32 v6, 3, v28
	v_ashrrev_i32_e32 v5, 31, v4
	v_ashrrev_i32_e32 v7, 31, v6
	v_ashrrev_i32_e32 v29, 3, v3
	v_lshlrev_b64 v[4:5], 10, v[4:5]
	v_lshlrev_b64 v[24:25], 1, v[6:7]
	v_mov_b64_e32 v[6:7], s[34:35]
	s_mov_b32 s3, 0
	s_cselect_b32 s2, 0x4000, 0
	v_lshl_add_u64 v[4:5], s[6:7], 0, v[4:5]
	v_mad_i64_i32 v[26:27], s[34:35], v29, s49, v[6:7]
	v_lshlrev_b32_e32 v0, 4, v3
	v_lshl_add_u64 v[4:5], v[4:5], 0, v[24:25]
	v_lshl_add_u64 v[6:7], v[26:27], 0, s[2:3]
	v_and_b32_e32 v0, 0x70, v0
	v_lshl_add_u64 v[6:7], v[6:7], 0, v[0:1]
	global_load_dwordx4 v[16:19], v[4:5], off
	global_load_dwordx4 v[20:23], v[6:7], off
	v_lshlrev_b32_e32 v31, 1, v3
	v_lshrrev_b32_e32 v32, 1, v3
	v_and_b32_e32 v33, 19, v3
	v_and_b32_e32 v31, 8, v31
	v_and_b32_e32 v32, 4, v32
	v_mul_lo_u32 v29, v29, s39
	v_or3_b32 v31, v33, v31, v32
	v_lshlrev_b32_e32 v30, 3, v140
	v_cmp_eq_u32_e32 vcc, 0, v2
	v_add3_u32 v123, 0, v29, v0
	v_mul_u32_u24_e32 v29, 0x90, v31
	v_mul_lo_u32 v31, v121, s39
	v_lshlrev_b32_e32 v28, 4, v28
	v_cndmask_b32_e32 v34, 0, v176, vcc
	v_mul_u32_u24_e32 v35, 0x90, v2
	v_mov_b32_e32 v14, v1
	v_mov_b32_e32 v15, v1
	v_lshlrev_b32_e32 v30, 1, v30
	s_mov_b32 s2, 0x5040100
	v_add3_u32 v125, 0, v31, v28
	v_mov_b32_e32 v2, v1
	v_mov_b32_e32 v3, v1
	v_mov_b32_e32 v4, v1
	v_mov_b32_e32 v5, v1
	v_mov_b32_e32 v6, v1
	v_mov_b32_e32 v7, v1
	v_mov_b32_e32 v8, v1
	v_mov_b32_e32 v9, v1
	v_mov_b32_e32 v10, v1
	v_mov_b32_e32 v11, v1
	v_mov_b32_e32 v12, v1
	v_mov_b32_e32 v13, v1
	v_perm_b32 v96, v34, v34, s2
	v_add3_u32 v120, 0, v35, v30
	v_add3_u32 v124, 0, v29, v30
	v_lshl_add_u64 v[116:117], s[6:7], 0, v[24:25]
	v_lshl_add_u64 v[118:119], v[26:27], 0, v[0:1]
	s_lshl_b32 s2, s10, 6
	v_mov_b32_e32 v0, v1
	v_mov_b64_e32 v[62:63], v[14:15]
	v_mov_b64_e32 v[46:47], v[14:15]
	v_mov_b32_e32 v122, 0xc2800000
	v_mov_b32_e32 v97, v96
	v_mov_b32_e32 v98, v96
	v_mov_b32_e32 v99, v96
	s_or_b32 s9, s9, 0x4040
	s_sub_i32 s15, 0, s2
	v_mov_b64_e32 v[60:61], v[12:13]
	v_mov_b64_e32 v[58:59], v[10:11]
	v_mov_b64_e32 v[56:57], v[8:9]
	v_mov_b64_e32 v[54:55], v[6:7]
	v_mov_b64_e32 v[52:53], v[4:5]
	v_mov_b64_e32 v[50:51], v[2:3]
	v_mov_b64_e32 v[48:49], v[0:1]
	v_mov_b64_e32 v[44:45], v[12:13]
	v_mov_b64_e32 v[42:43], v[10:11]
	s_waitcnt vmcnt(1)
	ds_write_b128 v125, v[16:19]
	s_waitcnt vmcnt(0)
	ds_write_b128 v123, v[20:23] offset:18432
	v_mov_b64_e32 v[30:31], v[14:15]
	v_mov_b64_e32 v[40:41], v[8:9]
	v_mov_b64_e32 v[38:39], v[6:7]
	v_mov_b64_e32 v[36:37], v[4:5]
	v_mov_b64_e32 v[34:35], v[2:3]
	v_mov_b64_e32 v[32:33], v[0:1]
	v_mov_b64_e32 v[28:29], v[12:13]
	v_mov_b64_e32 v[26:27], v[10:11]
	v_mov_b64_e32 v[24:25], v[8:9]
	v_mov_b64_e32 v[22:23], v[6:7]
	v_mov_b64_e32 v[20:21], v[4:5]
	v_mov_b64_e32 v[18:19], v[2:3]
	v_mov_b64_e32 v[16:17], v[0:1]
	s_waitcnt lgkmcnt(0)
	s_barrier
	s_add_i32 s34, s3, 1
	s_cmp_ge_u32 s34, s10
	s_mov_b64 s[6:7], -1
	s_cbranch_scc0 .LBB0_757
	s_branch .LBB0_756

.LBB0_766:
	s_andn2_b64 vcc, exec, s[6:7]
	s_cbranch_vccnz .LBB0_790
	s_mul_i32 s2, s12, 0x60
	s_lshl_b32 s6, s2, 1
	s_waitcnt vmcnt(0)
	v_mov_b32_e32 v17, v156
	s_add_u32 s2, s86, s6
	s_addc_u32 s3, s87, 0
	v_and_b32_e32 v16, 31, v17
	v_ashrrev_i32_e32 v4, 6, v17
	v_or_b32_e32 v0, s14, v16
	v_bfe_u32 v140, v17, 5, 1
	v_lshl_add_u32 v128, v4, 5, v0
	v_mov_b64_e32 v[2:3], s[2:3]
	s_movk_i32 s2, 0x300
	v_mad_i64_i32 v[2:3], s[2:3], v128, s2, v[2:3]
	v_lshlrev_b32_e32 v0, 4, v140
	v_lshl_add_u64 v[2:3], v[2:3], 0, v[0:1]
	global_load_dwordx4 v[120:123], v[2:3], off
	global_load_dwordx4 v[116:119], v[2:3], off offset:32
	global_load_dwordx4 v[112:115], v[2:3], off offset:64
	global_load_dwordx4 v[108:111], v[2:3], off offset:96
	global_load_dwordx4 v[104:107], v[2:3], off offset:128
	global_load_dwordx4 v[100:103], v[2:3], off offset:160
	v_cmp_lt_i32_e32 vcc, 3, v4
	s_and_saveexec_b64 s[2:3], vcc
	s_cbranch_execz .Lprio_skip_3
	s_setprio 1
.Lprio_skip_3:
	s_or_b64 exec, exec, s[2:3]
	v_readlane_b32 s2, v254, 42
	s_mov_b32 s9, 0x2aaaaaab
	s_add_u32 s6, s2, s6
	v_readlane_b32 s2, v254, 43
	v_mul_hi_i32 v0, v17, s9
	s_addc_u32 s7, s2, 0
	s_lshl_b32 s13, s13, 8
	v_lshrrev_b32_e32 v2, 31, v0
	v_ashrrev_i32_e32 v0, 1, v0
	v_add_u32_e32 v142, v0, v2
	s_or_b32 s8, s13, 0x4000
	v_mul_lo_u32 v0, v142, 12
	s_and_b64 s[2:3], exec, s[4:5]
	v_sub_u32_e32 v0, v17, v0
	s_cselect_b32 s14, s8, s11
	v_add_u32_e32 v4, s14, v142
	v_mov_b64_e32 v[2:3], s[6:7]
	s_movk_i32 s2, 0x300
	v_lshlrev_b32_e32 v10, 3, v0
	v_mad_i64_i32 v[2:3], s[2:3], v4, s2, v[2:3]
	v_ashrrev_i32_e32 v11, 31, v10
	v_lshl_add_u64 v[2:3], v[10:11], 1, v[2:3]
	global_load_dwordx4 v[2:5], v[2:3], off
	v_add_u32_e32 v0, 0x200, v17
	v_mul_hi_i32 v6, v0, s9
	v_lshrrev_b32_e32 v7, 31, v6
	v_ashrrev_i32_e32 v6, 1, v6
	v_add_u32_e32 v143, v6, v7
	v_mul_lo_u32 v6, v143, 12
	v_sub_u32_e32 v19, v0, v6
	v_mov_b32_e32 v0, v1
	v_lshlrev_b32_e32 v12, 3, v19
	v_cmp_lt_i32_e32 vcc, s38, v17
	v_cmp_gt_i32_e64 s[2:3], s46, v17
	v_ashrrev_i32_e32 v13, 31, v12
	v_mov_b64_e32 v[124:125], v[0:1]
	v_mov_b64_e32 v[126:127], v[0:1]
	s_and_saveexec_b64 s[8:9], s[2:3]
	s_cbranch_execz .LBB0_771
	v_add_u32_e32 v0, s14, v143
	v_mov_b64_e32 v[6:7], s[6:7]
	s_movk_i32 s14, 0x300
	v_mad_i64_i32 v[6:7], s[14:15], v0, s14, v[6:7]
	v_lshl_add_u64 v[6:7], v[12:13], 1, v[6:7]
	global_load_dwordx4 v[124:127], v[6:7], off
